# rwb: decay exponent exp(-softplus(-z)-0.5) evaluated in its closed form sigmoid(z)*exp(-0.5) (exact identity, f32, same f16 store); w0/a0 rows staged once per direction in LDS instead of per-step glob
# speedup vs baseline: 1.0179x; 1.0072x over previous
; __device__ __forceinline__ float tanhf_(float x) { const float e = __expf(2.0f * fminf(fmaxf(x, -15.f), 15.f)); return (e - 1.0f) * __builtin_amdgcn_rcpf(e + 1.0f); }
; __device__ __forceinline__ void phase_rwb(const int wvs, const Params& p, LAS unsigned char* lds, int layer) {
;     ...
;   for (int d = 0; d < 2; ++d) {
;     h8 bw[2], ba[2];
; #pragma unroll
;     for (int ks = 0; ks < 2; ++ks) { const h8 x = *(const h8*)(P + tok * PP + PC_RL2 + d * 64 + ks * 32 + fq * 8);
; #pragma unroll
;       for (int j = 0; j < 8; ++j) bw[ks][j] = (hf)tanhf_((float)x[j]);
;       ba[ks] = *(const h8*)(P + tok * PP + PC_RL2 + 128 + d * 64 + ks * 32 + fq * 8); }
;     { h8 sw[6], sa[6];
; #pragma unroll
;       for (int j = 0; j < 6; ++j) { const int idx = tid + 512 * j; const size_t wo = ((size_t)d * 384 + (idx >> 3)) * 64 + (idx & 7) * 8; sw[j] = *(const h8*)(wupT + wo); sa[j] = *(const h8*)(aupT + wo); }
;       __syncthreads();
.LBB0_1145:
	s_lshl_b32 s30, s6, 7
	v_lshl_add_u64 v[14:15], v[66:67], 0, s[30:31]
	global_load_dwordx4 v[2:5], v[14:15], off offset:3584
	s_mul_i32 s30, s6, 0x180
	v_lshl_add_u64 v[26:27], s[30:31], 0, v[70:71]
	v_lshlrev_b64 v[30:31], 7, v[26:27]
	v_or_b32_e32 v30, v30, v0
	v_lshl_add_u64 v[34:35], s[30:31], 0, v[72:73]
	v_lshl_add_u64 v[26:27], s[8:9], 0, v[30:31]
	v_lshlrev_b64 v[38:39], 7, v[34:35]
	v_lshl_add_u64 v[30:31], s[10:11], 0, v[30:31]
	v_or_b32_e32 v38, v38, v0
	v_lshl_add_u64 v[42:43], s[30:31], 0, v[74:75]
	v_lshl_add_u64 v[34:35], s[8:9], 0, v[38:39]
	v_lshlrev_b64 v[46:47], 7, v[42:43]
	v_lshl_add_u64 v[38:39], s[10:11], 0, v[38:39]
	v_or_b32_e32 v46, v46, v0
	v_lshl_add_u64 v[50:51], s[30:31], 0, v[76:77]
	v_lshl_add_u64 v[42:43], s[8:9], 0, v[46:47]
	v_lshlrev_b64 v[54:55], 7, v[50:51]
	v_lshl_add_u64 v[46:47], s[10:11], 0, v[46:47]
	v_or_b32_e32 v54, v54, v0
	v_lshl_add_u64 v[58:59], s[30:31], 0, v[78:79]
	v_lshl_add_u64 v[50:51], s[8:9], 0, v[54:55]
	v_lshlrev_b64 v[62:63], 7, v[58:59]
	v_lshl_add_u64 v[54:55], s[10:11], 0, v[54:55]
	v_or_b32_e32 v62, v62, v0
	v_lshl_add_u64 v[58:59], s[8:9], 0, v[62:63]
	v_lshl_add_u64 v[62:63], s[10:11], 0, v[62:63]
	s_or_b32 s2, s6, s16
	s_xor_b64 s[12:13], s[4:5], -1
	s_mov_b64 s[14:15], 0
	s_waitcnt vmcnt(0)
	v_cvt_f32_f16_e32 v6, v2
	v_cvt_f32_f16_sdwa v2, v2 dst_sel:DWORD dst_unused:UNUSED_PAD src0_sel:WORD_1
	v_med3_f32 v6, v6, s70, v223
	v_add_f32_e32 v6, v6, v6
	v_mul_f32_e32 v6, 0x3fb8aa3b, v6
	v_exp_f32_e32 v6, v6
	v_med3_f32 v2, v2, s70, v223
	v_add_f32_e32 v2, v2, v2
	v_mul_f32_e32 v2, 0x3fb8aa3b, v2
	v_add_f32_e32 v7, 1.0, v6
	v_rcp_f32_e32 v8, v7
	v_exp_f32_e32 v7, v2
	s_nop 0
	v_add_f32_e32 v2, 1.0, v7
	v_rcp_f32_e32 v9, v2
	v_pk_add_f32 v[6:7], v[6:7], -1.0 op_sel_hi:[1,0]
	s_nop 0
	v_pk_mul_f32 v[6:7], v[6:7], v[8:9]
	s_nop 0
	v_cvt_pk_f16_f32 v2, v6, v7
	v_cvt_f32_f16_e32 v6, v3
	v_cvt_f32_f16_sdwa v3, v3 dst_sel:DWORD dst_unused:UNUSED_PAD src0_sel:WORD_1
	v_med3_f32 v6, v6, s70, v223
	v_add_f32_e32 v6, v6, v6
	v_mul_f32_e32 v6, 0x3fb8aa3b, v6
	v_exp_f32_e32 v6, v6
	v_med3_f32 v3, v3, s70, v223
	v_add_f32_e32 v3, v3, v3
	v_mul_f32_e32 v3, 0x3fb8aa3b, v3
	v_add_f32_e32 v7, 1.0, v6
	v_rcp_f32_e32 v8, v7
	v_exp_f32_e32 v7, v3
	s_nop 0
	v_add_f32_e32 v3, 1.0, v7
	v_rcp_f32_e32 v9, v3
	v_pk_add_f32 v[6:7], v[6:7], -1.0 op_sel_hi:[1,0]
	s_nop 0
	v_pk_mul_f32 v[6:7], v[6:7], v[8:9]
	s_nop 0
	v_cvt_pk_f16_f32 v3, v6, v7
	v_cvt_f32_f16_e32 v6, v4
	v_cvt_f32_f16_sdwa v4, v4 dst_sel:DWORD dst_unused:UNUSED_PAD src0_sel:WORD_1
	v_med3_f32 v6, v6, s70, v223
	v_add_f32_e32 v6, v6, v6
	v_mul_f32_e32 v6, 0x3fb8aa3b, v6
	v_exp_f32_e32 v6, v6
	v_med3_f32 v4, v4, s70, v223
	v_add_f32_e32 v4, v4, v4
	v_mul_f32_e32 v4, 0x3fb8aa3b, v4
	v_add_f32_e32 v7, 1.0, v6
	v_rcp_f32_e32 v8, v7
	v_exp_f32_e32 v7, v4
	s_nop 0
	v_add_f32_e32 v4, 1.0, v7
	v_rcp_f32_e32 v9, v4
	v_pk_add_f32 v[6:7], v[6:7], -1.0 op_sel_hi:[1,0]
	s_nop 0
	v_pk_mul_f32 v[6:7], v[6:7], v[8:9]
	s_nop 0
	v_cvt_pk_f16_f32 v4, v6, v7
	v_cvt_f32_f16_e32 v6, v5
	v_cvt_f32_f16_sdwa v5, v5 dst_sel:DWORD dst_unused:UNUSED_PAD src0_sel:WORD_1
	v_med3_f32 v6, v6, s70, v223
	v_add_f32_e32 v6, v6, v6
	v_mul_f32_e32 v6, 0x3fb8aa3b, v6
	v_exp_f32_e32 v6, v6
	v_med3_f32 v5, v5, s70, v223
	v_add_f32_e32 v5, v5, v5
	v_mul_f32_e32 v5, 0x3fb8aa3b, v5
	v_add_f32_e32 v7, 1.0, v6
	v_rcp_f32_e32 v8, v7
	v_exp_f32_e32 v7, v5
	s_nop 0
	v_add_f32_e32 v5, 1.0, v7
	v_rcp_f32_e32 v9, v5
	v_pk_add_f32 v[6:7], v[6:7], -1.0 op_sel_hi:[1,0]
	s_nop 0
	v_pk_mul_f32 v[6:7], v[6:7], v[8:9]
	s_nop 0
	v_cvt_pk_f16_f32 v5, v6, v7
	global_load_dwordx4 v[6:9], v[14:15], off offset:3840
	global_load_dwordx4 v[10:13], v[14:15], off offset:3648
	s_waitcnt vmcnt(0)
	v_cvt_f32_f16_e32 v16, v10
	v_cvt_f32_f16_sdwa v10, v10 dst_sel:DWORD dst_unused:UNUSED_PAD src0_sel:WORD_1
	global_load_dwordx4 v[30:33], v[30:31], off
	v_med3_f32 v16, v16, s70, v223
	v_add_f32_e32 v16, v16, v16
	v_mul_f32_e32 v16, 0x3fb8aa3b, v16
	v_exp_f32_e32 v16, v16
	v_med3_f32 v10, v10, s70, v223
	v_add_f32_e32 v10, v10, v10
	v_mul_f32_e32 v10, 0x3fb8aa3b, v10
	v_add_f32_e32 v17, 1.0, v16
	v_rcp_f32_e32 v18, v17
	v_exp_f32_e32 v17, v10
	global_load_dwordx4 v[34:37], v[34:35], off
	v_add_f32_e32 v10, 1.0, v17
	v_rcp_f32_e32 v19, v10
	v_pk_add_f32 v[16:17], v[16:17], -1.0 op_sel_hi:[1,0]
	global_load_dwordx4 v[38:41], v[38:39], off
	v_pk_mul_f32 v[16:17], v[16:17], v[18:19]
	s_nop 0
	v_cvt_pk_f16_f32 v10, v16, v17
	v_cvt_f32_f16_e32 v16, v11
	v_cvt_f32_f16_sdwa v11, v11 dst_sel:DWORD dst_unused:UNUSED_PAD src0_sel:WORD_1
	global_load_dwordx4 v[42:45], v[42:43], off
	v_med3_f32 v16, v16, s70, v223
	v_add_f32_e32 v16, v16, v16
	v_mul_f32_e32 v16, 0x3fb8aa3b, v16
	v_exp_f32_e32 v16, v16
	v_med3_f32 v11, v11, s70, v223
	v_add_f32_e32 v11, v11, v11
	v_mul_f32_e32 v11, 0x3fb8aa3b, v11
	v_add_f32_e32 v17, 1.0, v16
	v_rcp_f32_e32 v18, v17
	v_exp_f32_e32 v17, v11
	global_load_dwordx4 v[46:49], v[46:47], off
	v_add_f32_e32 v11, 1.0, v17
	v_rcp_f32_e32 v19, v11
	v_pk_add_f32 v[16:17], v[16:17], -1.0 op_sel_hi:[1,0]
	global_load_dwordx4 v[50:53], v[50:51], off
	v_pk_mul_f32 v[16:17], v[16:17], v[18:19]
	s_nop 0
	v_cvt_pk_f16_f32 v11, v16, v17
	v_cvt_f32_f16_e32 v16, v12
	v_cvt_f32_f16_sdwa v12, v12 dst_sel:DWORD dst_unused:UNUSED_PAD src0_sel:WORD_1
	global_load_dwordx4 v[54:57], v[54:55], off
	v_med3_f32 v16, v16, s70, v223
	v_add_f32_e32 v16, v16, v16
	v_mul_f32_e32 v16, 0x3fb8aa3b, v16
	v_exp_f32_e32 v16, v16
	v_med3_f32 v12, v12, s70, v223
	v_add_f32_e32 v12, v12, v12
	v_mul_f32_e32 v12, 0x3fb8aa3b, v12
	v_add_f32_e32 v17, 1.0, v16
	v_rcp_f32_e32 v18, v17
	v_exp_f32_e32 v17, v12
	global_load_dwordx4 v[58:61], v[58:59], off
	v_add_f32_e32 v12, 1.0, v17
	v_rcp_f32_e32 v19, v12
	v_pk_add_f32 v[16:17], v[16:17], -1.0 op_sel_hi:[1,0]
	global_load_dwordx4 v[62:65], v[62:63], off
	v_pk_mul_f32 v[16:17], v[16:17], v[18:19]
	s_nop 0
	v_cvt_pk_f16_f32 v12, v16, v17
	v_cvt_f32_f16_e32 v16, v13
	v_cvt_f32_f16_sdwa v13, v13 dst_sel:DWORD dst_unused:UNUSED_PAD src0_sel:WORD_1
	global_load_dwordx4 v[26:29], v[26:27], off
	v_med3_f32 v16, v16, s70, v223
	v_add_f32_e32 v16, v16, v16
	v_mul_f32_e32 v16, 0x3fb8aa3b, v16
	v_exp_f32_e32 v16, v16
	v_med3_f32 v13, v13, s70, v223
	v_add_f32_e32 v13, v13, v13
	v_mul_f32_e32 v13, 0x3fb8aa3b, v13
	v_add_f32_e32 v17, 1.0, v16
	v_rcp_f32_e32 v18, v17
	v_exp_f32_e32 v17, v13
	s_nop 0
	v_add_f32_e32 v13, 1.0, v17
	v_rcp_f32_e32 v19, v13
	v_pk_add_f32 v[16:17], v[16:17], -1.0 op_sel_hi:[1,0]
	s_nop 0
	v_pk_mul_f32 v[16:17], v[16:17], v[18:19]
	v_lshl_add_u64 v[18:19], s[30:31], 0, v[68:69]
	v_lshlrev_b64 v[22:23], 7, v[18:19]
	v_or_b32_e32 v22, v22, v0
	v_lshl_add_u64 v[18:19], s[8:9], 0, v[22:23]
	v_cvt_pk_f16_f32 v13, v16, v17
	global_load_dwordx4 v[14:17], v[14:15], off offset:3904
	v_lshl_add_u64 v[22:23], s[10:11], 0, v[22:23]
	global_load_dwordx4 v[18:21], v[18:19], off
	s_mul_i32 s30, s2, 0x180
	global_load_dwordx4 v[22:25], v[22:23], off
	s_barrier
; #define LAS __attribute__((address_space(3)))
; __device__ __forceinline__ float sigmoidf_(float x) { return __builtin_amdgcn_rcpf(1.0f + __expf(-x)); }
; __device__ __forceinline__ float softplusf_(float x) { return x > 20.f ? x : __logf(1.0f + __expf(x)); }
; __device__ __forceinline__ f32x4 mfma16(h8 a, h8 b, f32x4 c) { return __builtin_amdgcn_mfma_f32_16x16x32_f16(a, b, c, 0, 0, 0); }
; __device__ __forceinline__ void phase_rwb(const int wvs, const Params& p, LAS unsigned char* lds, int layer) {
;     ...
;       __syncthreads();
; #pragma unroll
;       for (int j = 0; j < 6; ++j) { const int idx = tid + 512 * j; *(LAS h8*)(lds + (idx >> 3) * 144 + (idx & 7) * 16) = sw[j]; *(LAS h8*)(lds + 55296 + (idx >> 3) * 144 + (idx & 7) * 16) = sa[j]; }
;       __syncthreads(); }
;     const float* w0 = p.in[I_W0] + (layer * 2 + d) * 384; const float* a0 = p.in[I_A0] + (layer * 2 + d) * 384;
; #pragma unroll 2
;     for (int nt = 0; nt < 24; ++nt) { f32x4 aw = {0.f, 0.f, 0.f, 0.f}, aa = {0.f, 0.f, 0.f, 0.f};
;       const int n4 = nt * 16 + fq * 4; const f32x4 w04 = *(const f32x4*)(w0 + n4), a04 = *(const f32x4*)(a0 + n4);
; #pragma unroll
;       for (int ks = 0; ks < 2; ++ks) { aw = mfma16(*(const LAS h8*)(lds + (nt * 16 + fr) * 144 + ks * 64 + fq * 16), bw[ks], aw); aa = mfma16(*(const LAS h8*)(lds + 55296 + (nt * 16 + fr) * 144 + ks * 64 + fq * 16), ba[ks], aa); }
;       h4 oe, oa;
; #pragma unroll
;       for (int r = 0; r < 4; ++r) { const float wl = -softplusf_(-(w04[r] + aw[r])) - 0.5f; oe[r] = (hf)__expf(wl); oa[r] = (hf)sigmoidf_(a04[r] + aa[r]); }
;       *(h4*)(P + tok * PP + PC_EF + d * 384 + n4) = oe; *(h4*)(P + tok * PP + PC_AF + d * 384 + n4) = oa; }
	s_waitcnt vmcnt(1)
	ds_write_b128 v87, v[18:21]
	s_waitcnt vmcnt(0)
	ds_write_b128 v87, v[22:25] offset:55296
	ds_write_b128 v88, v[26:29]
	ds_write_b128 v88, v[30:33] offset:55296
	ds_write_b128 v89, v[34:37]
	ds_write_b128 v89, v[38:41] offset:55296
	ds_write_b128 v90, v[42:45]
	ds_write_b128 v90, v[46:49] offset:55296
	ds_write_b128 v91, v[50:53]
	ds_write_b128 v91, v[54:57] offset:55296
	ds_write_b128 v92, v[58:61]
	ds_write_b128 v92, v[62:65] offset:55296
	v_mov_b32_e32 v18, 0x300
	v_mad_u64_u32 v[26:27], s[4:5], s6, v18, v[80:81]
	s_lshl_b64 s[4:5], s[30:31], 2
	s_nop 0
	v_lshl_add_u64 v[28:29], v[82:83], 0, s[4:5]
	v_lshl_add_u64 v[30:31], v[84:85], 0, s[4:5]
	v_mov_b32_e32 v32, v86
	v_readfirstlane_b32 s4, v30
	v_readfirstlane_b32 s5, v31
	v_min_u32_e32 v104, 0x5f, v193
	v_lshlrev_b32_e32 v104, 4, v104
	v_and_b32_e32 v106, 48, v193
	v_add_u32_e32 v105, 0x1b800, v104
	v_add_u32_e32 v106, 0x1b800, v106
	s_nop 1
	global_load_dwordx4 v[96:99], v104, s[4:5]
	v_readfirstlane_b32 s4, v28
	v_readfirstlane_b32 s5, v29
	s_nop 4
	global_load_dwordx4 v[100:103], v104, s[4:5]
	s_waitcnt vmcnt(0)
	ds_write_b128 v105, v[96:99]
	ds_write_b128 v105, v[100:103] offset:1536
	s_waitcnt lgkmcnt(0)
	s_barrier
.LBB0_1146:
	ds_read_b128 v[18:21], v106
	ds_read_b128 v[22:25], v106 offset:1536
	ds_read_b128 v[34:37], v32
	ds_read_b128 v[42:45], v32 offset:64
	ds_read_b128 v[38:41], v32 offset:55296
	s_add_u32 s14, s14, 0x80
	s_addc_u32 s15, s15, 0
	s_waitcnt lgkmcnt(2)
	v_mfma_f32_16x16x32_f16 v[34:37], v[34:37], v[2:5], 0
	s_cmpk_eq_i32 s14, 0x600
	s_waitcnt lgkmcnt(1)
	v_mfma_f32_16x16x32_f16 v[34:37], v[42:45], v[10:13], v[34:37]
	ds_read_b128 v[42:45], v32 offset:55360
	s_waitcnt lgkmcnt(1)
	v_mfma_f32_16x16x32_f16 v[38:41], v[38:41], v[6:9], 0
	s_waitcnt lgkmcnt(0)
	v_mfma_f32_16x16x32_f16 v[38:41], v[42:45], v[14:17], v[38:41]
	s_nop 0
	s_nop 1
	v_add_f32_e32 v18, v18, v34
	v_add_f32_e32 v19, v19, v35
	v_add_f32_e32 v20, v20, v36
	v_add_f32_e32 v21, v21, v37
	v_mul_f32_e32 v18, 0xbfb8aa3b, v18
	v_mul_f32_e32 v19, 0xbfb8aa3b, v19
	v_mul_f32_e32 v20, 0xbfb8aa3b, v20
	v_mul_f32_e32 v21, 0xbfb8aa3b, v21
	v_exp_f32_e32 v18, v18
	v_exp_f32_e32 v19, v19
	v_exp_f32_e32 v20, v20
	v_exp_f32_e32 v21, v21
	v_add_f32_e32 v18, 1.0, v18
	v_add_f32_e32 v19, 1.0, v19
	v_add_f32_e32 v20, 1.0, v20
	v_add_f32_e32 v21, 1.0, v21
	v_add_f32_e32 v22, v22, v38
	v_add_f32_e32 v23, v23, v39
	v_add_f32_e32 v24, v24, v40
	v_add_f32_e32 v25, v25, v41
	v_mul_f32_e32 v22, 0xbfb8aa3b, v22
	v_mul_f32_e32 v23, 0xbfb8aa3b, v23
	v_mul_f32_e32 v24, 0xbfb8aa3b, v24
	v_mul_f32_e32 v25, 0xbfb8aa3b, v25
	v_exp_f32_e32 v22, v22
	v_exp_f32_e32 v23, v23
	v_exp_f32_e32 v24, v24
	v_exp_f32_e32 v25, v25
	v_rcp_f32_e32 v18, v18
	v_rcp_f32_e32 v19, v19
	v_rcp_f32_e32 v20, v20
	v_rcp_f32_e32 v21, v21
	v_add_f32_e32 v22, 1.0, v22
	v_add_f32_e32 v23, 1.0, v23
	v_add_f32_e32 v24, 1.0, v24
	v_add_f32_e32 v25, 1.0, v25
	v_rcp_f32_e32 v22, v22
	v_rcp_f32_e32 v23, v23
	v_rcp_f32_e32 v24, v24
	v_rcp_f32_e32 v25, v25
	v_mul_f32_e32 v18, 0x3f1b4598, v18
	v_mul_f32_e32 v19, 0x3f1b4598, v19
	v_mul_f32_e32 v20, 0x3f1b4598, v20
	v_mul_f32_e32 v21, 0x3f1b4598, v21
	v_cvt_pk_f16_f32 v18, v18, v19
	v_cvt_pk_f16_f32 v19, v20, v21
	v_cvt_pk_f16_f32 v20, v22, v23
	v_cvt_pk_f16_f32 v21, v24, v25
	global_store_dwordx2 v[26:27], v[18:19], off offset:-1536
	global_store_dwordx2 v[26:27], v[20:21], off
	ds_read_b128 v[22:25], v106 offset:64
	ds_read_b128 v[18:21], v106 offset:1600
	ds_read_b128 v[34:37], v32 offset:2304
	ds_read_b128 v[42:45], v32 offset:2368
	s_waitcnt lgkmcnt(1)
	v_mfma_f32_16x16x32_f16 v[34:37], v[34:37], v[2:5], 0
	ds_read_b128 v[38:41], v32 offset:57600
	s_waitcnt lgkmcnt(1)
	v_mfma_f32_16x16x32_f16 v[34:37], v[42:45], v[10:13], v[34:37]
	ds_read_b128 v[42:45], v32 offset:57664
	v_add_u32_e32 v32, 0x1200, v32
	s_waitcnt lgkmcnt(1)
	v_mfma_f32_16x16x32_f16 v[38:41], v[38:41], v[6:9], 0
	s_nop 0
	s_nop 2
	v_add_f32_e32 v22, v22, v34
	v_add_f32_e32 v23, v23, v35
	v_add_f32_e32 v24, v24, v36
	v_add_f32_e32 v25, v25, v37
	s_waitcnt lgkmcnt(0)
	v_mfma_f32_16x16x32_f16 v[38:41], v[42:45], v[14:17], v[38:41]
	v_mul_f32_e32 v22, 0xbfb8aa3b, v22
	v_mul_f32_e32 v23, 0xbfb8aa3b, v23
	v_mul_f32_e32 v24, 0xbfb8aa3b, v24
	v_mul_f32_e32 v25, 0xbfb8aa3b, v25
	v_exp_f32_e32 v22, v22
	v_exp_f32_e32 v23, v23
	v_exp_f32_e32 v24, v24
	v_exp_f32_e32 v25, v25
	v_add_f32_e32 v22, 1.0, v22
	v_add_f32_e32 v23, 1.0, v23
	v_add_f32_e32 v24, 1.0, v24
	v_add_f32_e32 v25, 1.0, v25
	v_add_f32_e32 v38, v18, v38
	v_add_f32_e32 v39, v19, v39
	v_add_f32_e32 v40, v20, v40
	v_add_f32_e32 v41, v21, v41
	v_mul_f32_e32 v38, 0xbfb8aa3b, v38
	v_mul_f32_e32 v39, 0xbfb8aa3b, v39
	v_mul_f32_e32 v40, 0xbfb8aa3b, v40
	v_mul_f32_e32 v41, 0xbfb8aa3b, v41
	v_exp_f32_e32 v38, v38
	v_exp_f32_e32 v39, v39
	v_exp_f32_e32 v40, v40
	v_exp_f32_e32 v41, v41
	v_rcp_f32_e32 v22, v22
	v_rcp_f32_e32 v23, v23
	v_rcp_f32_e32 v24, v24
	v_rcp_f32_e32 v25, v25
	v_add_f32_e32 v38, 1.0, v38
	v_add_f32_e32 v39, 1.0, v39
	v_add_f32_e32 v40, 1.0, v40
	v_add_f32_e32 v41, 1.0, v41
	v_rcp_f32_e32 v38, v38
	v_rcp_f32_e32 v39, v39
	v_rcp_f32_e32 v40, v40
	v_rcp_f32_e32 v41, v41
	v_mul_f32_e32 v22, 0x3f1b4598, v22
	v_mul_f32_e32 v23, 0x3f1b4598, v23
	v_mul_f32_e32 v24, 0x3f1b4598, v24
	v_mul_f32_e32 v25, 0x3f1b4598, v25
	v_cvt_pk_f16_f32 v18, v22, v23
	v_cvt_pk_f16_f32 v19, v24, v25
	v_cvt_pk_f16_f32 v20, v38, v39
	v_cvt_pk_f16_f32 v21, v40, v41
	global_store_dwordx2 v[26:27], v[18:19], off offset:-1504
	global_store_dwordx2 v[26:27], v[20:21], off offset:32
	v_lshl_add_u64 v[26:27], v[26:27], 0, 64
	v_add_u32_e32 v106, 0x80, v106
	s_cbranch_scc0 .LBB0_1146
	s_mov_b32 s6, 1
	s_mov_b64 s[4:5], 0
	s_and_b64 vcc, exec, s[12:13]
	s_cbranch_vccz .LBB0_1145
